# stack on v3: preheader drains removed, XCD barrier leader publishes release before its own L1 invalidate, FoX prompt bias as v_fma instead of v_xor+v_pk_fma
# speedup vs baseline: 1.0078x; 1.0078x over previous
.LBB0_111:
	s_or_b64 exec, exec, s[4:5]
	s_mov_b64 s[4:5], exec
	v_mbcnt_lo_u32_b32 v1, s4, 0
	v_mbcnt_hi_u32_b32 v1, s5, v1
	v_cmp_eq_u32_e32 vcc, 0, v1
	s_waitcnt vmcnt(0)
	s_nop 0
	s_and_saveexec_b64 s[6:7], vcc
	s_cbranch_execz .LBB0_113
	s_bcnt1_i32_b64 s4, s[4:5]
	v_mov_b32_e32 v1, 0x2000
	v_mov_b32_e32 v2, s4
	global_atomic_add v1, v2, s[2:3] offset:1024
.LBB0_113:
	s_or_b64 exec, exec, s[6:7]
	buffer_inv sc1
	s_waitcnt vmcnt(0)

.LBB0_415:
	s_or_b64 exec, exec, s[8:9]
	s_mov_b64 s[8:9], exec
	v_mbcnt_lo_u32_b32 v1, s8, 0
	v_mbcnt_hi_u32_b32 v1, s9, v1
	v_cmp_eq_u32_e32 vcc, 0, v1
	s_waitcnt vmcnt(0)
	s_nop 0
	s_and_saveexec_b64 s[10:11], vcc
	s_cbranch_execz .LBB0_417
	s_bcnt1_i32_b64 s2, s[8:9]
	v_mov_b32_e32 v1, s2
	v_mov_b32_e32 v2, 0x2000
	global_atomic_add v2, v1, s[6:7] offset:1024
.LBB0_417:
	s_or_b64 exec, exec, s[10:11]
	buffer_inv sc1
	s_waitcnt vmcnt(0)

.LBB0_720:
	s_lshl_b32 s37, s89, 14
	v_add_u32_e32 v2, s37, v137
	v_add_u32_e32 v3, v2, v146
	ds_read_b128 v[70:73], v3
	ds_read_b128 v[74:77], v3 offset:8192
	v_add_u32_e32 v3, v2, v147
	ds_read_b128 v[160:163], v3
	ds_read_b128 v[164:167], v3 offset:8192
	v_add_u32_e32 v3, v2, v148
	ds_read_b128 v[168:171], v3
	ds_read_b128 v[172:175], v3 offset:8192
	v_add_u32_e32 v3, v2, v149
	ds_read_b128 v[176:179], v3
	ds_read_b128 v[180:183], v3 offset:8192
	v_add_u32_e32 v3, v2, v150
	ds_read_b128 v[184:187], v3
	ds_read_b128 v[188:191], v3 offset:8192
	v_add_u32_e32 v3, v2, v151
	ds_read_b128 v[192:195], v3
	ds_read_b128 v[196:199], v3 offset:8192
	v_add_u32_e32 v3, v2, v152
	v_add_u32_e32 v2, v2, v153
	ds_read_b128 v[200:203], v3
	ds_read_b128 v[204:207], v3 offset:8192
	ds_read_b128 v[208:211], v2
	ds_read_b128 v[216:219], v2 offset:8192
	s_waitcnt lgkmcnt(0)
	v_mfma_f32_32x32x16_bf16 v[86:101], v[70:73], v[102:105], 0
	v_mfma_f32_32x32x16_bf16 v[70:85], v[74:77], v[102:105], 0
	v_mfma_f32_32x32x16_bf16 v[86:101], v[160:163], v[106:109], v[86:101]
	v_mfma_f32_32x32x16_bf16 v[70:85], v[164:167], v[106:109], v[70:85]
	v_mfma_f32_32x32x16_bf16 v[86:101], v[168:171], v[110:113], v[86:101]
	v_mfma_f32_32x32x16_bf16 v[70:85], v[172:175], v[110:113], v[70:85]
	v_mfma_f32_32x32x16_bf16 v[86:101], v[176:179], v[114:117], v[86:101]
	v_mfma_f32_32x32x16_bf16 v[70:85], v[180:183], v[114:117], v[70:85]
	v_mfma_f32_32x32x16_bf16 v[86:101], v[184:187], v[118:121], v[86:101]
	v_mfma_f32_32x32x16_bf16 v[70:85], v[188:191], v[118:121], v[70:85]
	v_mfma_f32_32x32x16_bf16 v[86:101], v[192:195], v[122:125], v[86:101]
	v_mfma_f32_32x32x16_bf16 v[70:85], v[196:199], v[122:125], v[70:85]
	v_mfma_f32_32x32x16_bf16 v[86:101], v[200:203], v[126:129], v[86:101]
	v_mfma_f32_32x32x16_bf16 v[70:85], v[204:207], v[126:129], v[70:85]
	v_mfma_f32_32x32x16_bf16 v[86:101], v[208:211], v[130:133], v[86:101]
	v_mfma_f32_32x32x16_bf16 v[70:85], v[216:219], v[130:133], v[70:85]
	v_add_u32_e32 v2, s70, v155
	v_add_u32_e32 v3, 0x1e000, v2
	v_add_u32_e32 v5, 0x1e080, v2
	ds_read_b128 v[160:163], v3
	ds_read_b128 v[164:167], v5
	v_add_u32_e32 v3, 0x1e020, v2
	v_add_u32_e32 v5, 0x1e0a0, v2
	ds_read_b128 v[168:171], v3
	ds_read_b128 v[172:175], v5
	v_add_u32_e32 v3, 0x1e040, v2
	v_add_u32_e32 v5, 0x1e0c0, v2
	ds_read_b128 v[176:179], v3
	ds_read_b128 v[180:183], v5
	v_add_u32_e32 v3, 0x1e060, v2
	v_add_u32_e32 v2, 0x1e0e0, v2
	ds_read_b128 v[184:187], v3
	ds_read_b128 v[188:191], v2
	s_waitcnt lgkmcnt(0)
	v_fma_f32 v2, v100, s86, -v186
	v_fma_f32 v3, v101, s86, -v187
	v_fma_f32 v88, v88, s86, -v162
	v_fma_f32 v89, v89, s86, -v163
	v_fma_f32 v86, v86, s86, -v160
	v_fma_f32 v87, v87, s86, -v161
	v_fma_f32 v98, v98, s86, -v184
	v_fma_f32 v99, v99, s86, -v185
	v_fma_f32 v96, v96, s86, -v178
	v_fma_f32 v97, v97, s86, -v179
	v_fma_f32 v94, v94, s86, -v176
	v_fma_f32 v95, v95, s86, -v177
	v_fma_f32 v92, v92, s86, -v170
	v_fma_f32 v93, v93, s86, -v171
	v_fma_f32 v90, v90, s86, -v168
	v_fma_f32 v91, v91, s86, -v169
	v_fma_f32 v84, v84, s86, -v190
	v_fma_f32 v85, v85, s86, -v191
	v_fma_f32 v82, v82, s86, -v188
	v_fma_f32 v83, v83, s86, -v189
	v_fma_f32 v80, v80, s86, -v182
	v_fma_f32 v81, v81, s86, -v183
	v_fma_f32 v78, v78, s86, -v180
	v_fma_f32 v79, v79, s86, -v181
	v_fma_f32 v76, v76, s86, -v174
	v_fma_f32 v77, v77, s86, -v175
	v_fma_f32 v74, v74, s86, -v172
	v_fma_f32 v75, v75, s86, -v173
	v_fma_f32 v72, v72, s86, -v166
	v_fma_f32 v73, v73, s86, -v167
	s_cmp_le_i32 s85, s95
	v_fma_f32 v70, v70, s86, -v164
	v_fma_f32 v71, v71, s86, -v165
	s_cbranch_scc1 .LBB0_722
	v_cmp_gt_i32_e64 s[66:67], 26, v156
	v_cmp_gt_i32_e64 s[68:69], 27, v156
	v_cmp_gt_i32_e64 s[64:65], 25, v156
	s_and_b64 s[66:67], s[68:69], s[66:67]
	v_cmp_gt_i32_e64 s[62:63], 24, v156
	s_and_b64 s[64:65], s[66:67], s[64:65]
	v_cmp_gt_i32_e64 s[60:61], 19, v156
	s_and_b64 s[62:63], s[64:65], s[62:63]
	v_cmp_gt_i32_e64 s[58:59], 18, v156
	s_and_b64 s[60:61], s[62:63], s[60:61]
	v_cmp_gt_i32_e64 s[56:57], 17, v156
	s_and_b64 s[58:59], s[60:61], s[58:59]
	v_cmp_gt_i32_e64 s[54:55], 16, v156
	s_and_b64 s[56:57], s[58:59], s[56:57]
	v_cmp_gt_i32_e64 s[52:53], 11, v156
	s_and_b64 s[54:55], s[56:57], s[54:55]
	v_cmp_gt_i32_e64 s[50:51], 10, v156
	s_and_b64 s[52:53], s[54:55], s[52:53]
	v_cmp_gt_i32_e64 s[48:49], 9, v156
	s_and_b64 s[50:51], s[52:53], s[50:51]
	v_cmp_gt_i32_e64 s[46:47], 8, v156
	s_and_b64 s[48:49], s[50:51], s[48:49]
	v_cmp_gt_i32_e64 s[44:45], 3, v156
	s_and_b64 s[46:47], s[48:49], s[46:47]
	v_cmp_gt_i32_e64 s[42:43], 2, v156
	s_and_b64 s[44:45], s[46:47], s[44:45]
	v_cmp_gt_i32_e64 s[40:41], 1, v156
	s_and_b64 s[42:43], s[44:45], s[42:43]
	v_cmp_gt_i32_e64 s[0:1], 0, v156
	s_and_b64 s[40:41], s[42:43], s[40:41]
	s_and_b64 s[0:1], s[40:41], s[0:1]
	v_cmp_gt_i32_e64 s[34:35], 58, v156
	v_cndmask_b32_e64 v86, v86, v247, s[0:1]
	v_cmp_gt_i32_e64 s[0:1], 59, v156
	v_cmp_gt_i32_e64 s[30:31], 57, v156
	v_cmp_gt_i32_e64 s[28:29], 56, v156
	v_cndmask_b32_e64 v85, v85, v247, s[0:1]
	s_and_b64 s[0:1], s[0:1], s[34:35]
	v_cndmask_b32_e64 v84, v84, v247, s[0:1]
	s_and_b64 s[0:1], s[0:1], s[30:31]
	v_cmp_gt_i32_e64 s[26:27], 51, v156
	v_cndmask_b32_e64 v83, v83, v247, s[0:1]
	s_and_b64 s[0:1], s[0:1], s[28:29]
	v_cmp_gt_i32_e64 s[24:25], 50, v156
	v_cndmask_b32_e64 v82, v82, v247, s[0:1]
	s_and_b64 s[0:1], s[0:1], s[26:27]
	v_cmp_gt_i32_e64 s[22:23], 49, v156
	v_cndmask_b32_e64 v81, v81, v247, s[0:1]
	s_and_b64 s[0:1], s[0:1], s[24:25]
	v_cmp_gt_i32_e64 s[20:21], 48, v156
	v_cndmask_b32_e64 v80, v80, v247, s[0:1]
	s_and_b64 s[0:1], s[0:1], s[22:23]
	v_cmp_gt_i32_e64 s[18:19], 43, v156
	v_cndmask_b32_e64 v79, v79, v247, s[0:1]
	s_and_b64 s[0:1], s[0:1], s[20:21]
	v_cmp_gt_i32_e64 s[16:17], 42, v156
	v_cndmask_b32_e64 v78, v78, v247, s[0:1]
	s_and_b64 s[0:1], s[0:1], s[18:19]
	v_cmp_gt_i32_e64 s[14:15], 41, v156
	v_cndmask_b32_e64 v77, v77, v247, s[0:1]
	s_and_b64 s[0:1], s[0:1], s[16:17]
	v_cmp_gt_i32_e64 s[12:13], 40, v156
	v_cndmask_b32_e64 v76, v76, v247, s[0:1]
	s_and_b64 s[0:1], s[0:1], s[14:15]
	v_cmp_gt_i32_e64 s[10:11], 35, v156
	v_cndmask_b32_e64 v75, v75, v247, s[0:1]
	s_and_b64 s[0:1], s[0:1], s[12:13]
	v_cmp_gt_i32_e64 s[8:9], 34, v156
	v_cndmask_b32_e64 v74, v74, v247, s[0:1]
	s_and_b64 s[0:1], s[0:1], s[10:11]
	v_cmp_gt_i32_e64 s[6:7], 33, v156
	v_cndmask_b32_e64 v73, v73, v247, s[0:1]
	s_and_b64 s[0:1], s[0:1], s[8:9]
	v_cmp_gt_i32_e32 vcc, 32, v156
	v_cndmask_b32_e64 v72, v72, v247, s[0:1]
	s_and_b64 s[0:1], s[0:1], s[6:7]
	s_and_b64 vcc, s[0:1], vcc
	v_cndmask_b32_e64 v3, v3, v247, s[68:69]
	v_cndmask_b32_e64 v2, v2, v247, s[66:67]
	v_cndmask_b32_e64 v99, v99, v247, s[64:65]
	v_cndmask_b32_e64 v98, v98, v247, s[62:63]
	v_cndmask_b32_e64 v97, v97, v247, s[60:61]
	v_cndmask_b32_e64 v96, v96, v247, s[58:59]
	v_cndmask_b32_e64 v95, v95, v247, s[56:57]
	v_cndmask_b32_e64 v94, v94, v247, s[54:55]
	v_cndmask_b32_e64 v93, v93, v247, s[52:53]
	v_cndmask_b32_e64 v92, v92, v247, s[50:51]
	s_mov_b32 s51, 0x40c000
	v_cndmask_b32_e64 v91, v91, v247, s[48:49]
	s_mov_b64 s[48:49], 0x7ffff
	v_cndmask_b32_e64 v90, v90, v247, s[46:47]
	s_mov_b32 s47, 0x120000
	v_cndmask_b32_e64 v89, v89, v247, s[44:45]
	v_cndmask_b32_e64 v88, v88, v247, s[42:43]
	v_cndmask_b32_e64 v87, v87, v247, s[40:41]
	s_mov_b32 s40, 0x41000000
	v_cndmask_b32_e64 v71, v71, v247, s[0:1]
	v_cndmask_b32_e32 v70, v70, v247, vcc
